# hyena context item: convolution taps read from LDS in batches of 8 instead of one round trip per tap (same fmac order)
# speedup vs baseline: 1.0298x; 1.0010x over previous
; DI u16 f2bf(float a) { return (u16)(pack2(a, 0.f) & 0xffffu); }
; DI void hyena_ctx_item(const P& p, int l, int c, unsigned char* lds) {
;     ...
;     __syncthreads();
;     sv[bb * 256 + t] = o[0];
;     __syncthreads();
;     float a = 0.f;
;     for (int s2 = 0; s2 < 256; ++s2) a += f0[(t - s2) & 511] * sv[bb * 256 + s2];
;     float y1 = o[1] * (a + o[0] * bias0);
;     __syncthreads();
;     sv[bb * 256 + t] = y1;
;     __syncthreads();
;     float a2 = 0.f;
;     for (int s2 = 0; s2 < 256; ++s2) a2 += f1[(t - s2) & 511] * sv[bb * 256 + s2];
;     HY[(rb + t) * 256 + c] = f2bf(o[2] * (a2 + y1 * bias1));
.LBB0_325:
	v_add_u32_e32 v11, s34, v2
	ds_read_b128 v[18:21], v10
	ds_read_b128 v[22:25], v10 offset:16
	ds_read_b128 v[26:29], v10 offset:32
	ds_read_b128 v[30:33], v10 offset:48
	v_add_u32_e32 v130, 0xffffff00, v11
	v_add_u32_e32 v131, 0xfffffeff, v11
	v_add_u32_e32 v132, 0xfffffefe, v11
	v_add_u32_e32 v133, 0xfffffefd, v11
	v_add_u32_e32 v134, 0xfffffefc, v11
	v_add_u32_e32 v135, 0xfffffefb, v11
	v_add_u32_e32 v136, 0xfffffefa, v11
	v_add_u32_e32 v137, 0xfffffef9, v11
	v_and_b32_e32 v130, 0x1ff, v130
	v_and_b32_e32 v131, 0x1ff, v131
	v_and_b32_e32 v132, 0x1ff, v132
	v_and_b32_e32 v133, 0x1ff, v133
	v_and_b32_e32 v134, 0x1ff, v134
	v_and_b32_e32 v135, 0x1ff, v135
	v_and_b32_e32 v136, 0x1ff, v136
	v_and_b32_e32 v137, 0x1ff, v137
	v_lshl_add_u32 v130, v130, 2, 0
	v_lshl_add_u32 v131, v131, 2, 0
	v_lshl_add_u32 v132, v132, 2, 0
	v_lshl_add_u32 v133, v133, 2, 0
	v_lshl_add_u32 v134, v134, 2, 0
	v_lshl_add_u32 v135, v135, 2, 0
	v_lshl_add_u32 v136, v136, 2, 0
	v_lshl_add_u32 v137, v137, 2, 0
	ds_read_b32 v130, v130
	ds_read_b32 v131, v131
	ds_read_b32 v132, v132
	ds_read_b32 v133, v133
	ds_read_b32 v134, v134
	ds_read_b32 v135, v135
	ds_read_b32 v136, v136
	ds_read_b32 v137, v137
	s_add_i32 s34, s34, -16
	v_add_u32_e32 v10, 64, v10
	s_cmp_eq_u32 s34, 0
	s_waitcnt lgkmcnt(7)
	v_fmac_f32_e32 v9, v130, v18
	s_waitcnt lgkmcnt(6)
	v_fmac_f32_e32 v9, v131, v19
	s_waitcnt lgkmcnt(5)
	v_fmac_f32_e32 v9, v132, v20
	s_waitcnt lgkmcnt(4)
	v_fmac_f32_e32 v9, v133, v21
	s_waitcnt lgkmcnt(3)
	v_fmac_f32_e32 v9, v134, v22
	s_waitcnt lgkmcnt(2)
	v_fmac_f32_e32 v9, v135, v23
	s_waitcnt lgkmcnt(1)
	v_fmac_f32_e32 v9, v136, v24
	s_waitcnt lgkmcnt(0)
	v_fmac_f32_e32 v9, v137, v25
	v_add_u32_e32 v138, 0xfffffef8, v11
	v_add_u32_e32 v139, 0xfffffef7, v11
	v_add_u32_e32 v140, 0xfffffef6, v11
	v_add_u32_e32 v141, 0xfffffef5, v11
	v_add_u32_e32 v142, 0xfffffef4, v11
	v_add_u32_e32 v143, 0xfffffef3, v11
	v_add_u32_e32 v144, 0xfffffef2, v11
	v_add_u32_e32 v145, 0xfffffef1, v11
	v_and_b32_e32 v138, 0x1ff, v138
	v_and_b32_e32 v139, 0x1ff, v139
	v_and_b32_e32 v140, 0x1ff, v140
	v_and_b32_e32 v141, 0x1ff, v141
	v_and_b32_e32 v142, 0x1ff, v142
	v_and_b32_e32 v143, 0x1ff, v143
	v_and_b32_e32 v144, 0x1ff, v144
	v_and_b32_e32 v145, 0x1ff, v145
	v_lshl_add_u32 v138, v138, 2, 0
	v_lshl_add_u32 v139, v139, 2, 0
	v_lshl_add_u32 v140, v140, 2, 0
	v_lshl_add_u32 v141, v141, 2, 0
	v_lshl_add_u32 v142, v142, 2, 0
	v_lshl_add_u32 v143, v143, 2, 0
	v_lshl_add_u32 v144, v144, 2, 0
	v_lshl_add_u32 v145, v145, 2, 0
	ds_read_b32 v138, v138
	ds_read_b32 v139, v139
	ds_read_b32 v140, v140
	ds_read_b32 v141, v141
	ds_read_b32 v142, v142
	ds_read_b32 v143, v143
	ds_read_b32 v144, v144
	ds_read_b32 v145, v145
	s_waitcnt lgkmcnt(7)
	v_fmac_f32_e32 v9, v138, v26
	s_waitcnt lgkmcnt(6)
	v_fmac_f32_e32 v9, v139, v27
	s_waitcnt lgkmcnt(5)
	v_fmac_f32_e32 v9, v140, v28
	s_waitcnt lgkmcnt(4)
	v_fmac_f32_e32 v9, v141, v29
	s_waitcnt lgkmcnt(3)
	v_fmac_f32_e32 v9, v142, v30
	s_waitcnt lgkmcnt(2)
	v_fmac_f32_e32 v9, v143, v31
	s_waitcnt lgkmcnt(1)
	v_fmac_f32_e32 v9, v144, v32
	s_waitcnt lgkmcnt(0)
	v_fmac_f32_e32 v9, v145, v33
	s_cbranch_scc0 .LBB0_325
	v_fmac_f32_e32 v9, v3, v16
	v_mul_f32_e32 v9, v17, v9
	v_mov_b32_e32 v10, 0
	s_movk_i32 s34, 0x100
	v_mov_b32_e32 v11, v15
	s_barrier
	ds_write_b32 v1, v9 offset:4096
	s_waitcnt lgkmcnt(0)
	s_barrier
.LBB0_327:
	v_add_u32_e32 v12, s34, v2
	ds_read_b128 v[16:19], v11
	ds_read_b128 v[20:23], v11 offset:16
	ds_read_b128 v[24:27], v11 offset:32
	ds_read_b128 v[28:31], v11 offset:48
	v_add_u32_e32 v130, 0xffffff00, v12
	v_add_u32_e32 v131, 0xfffffeff, v12
	v_add_u32_e32 v132, 0xfffffefe, v12
	v_add_u32_e32 v133, 0xfffffefd, v12
	v_add_u32_e32 v134, 0xfffffefc, v12
	v_add_u32_e32 v135, 0xfffffefb, v12
	v_add_u32_e32 v136, 0xfffffefa, v12
	v_add_u32_e32 v137, 0xfffffef9, v12
	v_and_b32_e32 v130, 0x1ff, v130
	v_and_b32_e32 v131, 0x1ff, v131
	v_and_b32_e32 v132, 0x1ff, v132
	v_and_b32_e32 v133, 0x1ff, v133
	v_and_b32_e32 v134, 0x1ff, v134
	v_and_b32_e32 v135, 0x1ff, v135
	v_and_b32_e32 v136, 0x1ff, v136
	v_and_b32_e32 v137, 0x1ff, v137
	v_lshl_add_u32 v130, v130, 2, 0
	v_lshl_add_u32 v131, v131, 2, 0
	v_lshl_add_u32 v132, v132, 2, 0
	v_lshl_add_u32 v133, v133, 2, 0
	v_lshl_add_u32 v134, v134, 2, 0
	v_lshl_add_u32 v135, v135, 2, 0
	v_lshl_add_u32 v136, v136, 2, 0
	v_lshl_add_u32 v137, v137, 2, 0
	ds_read_b32 v130, v130 offset:2048
	ds_read_b32 v131, v131 offset:2048
	ds_read_b32 v132, v132 offset:2048
	ds_read_b32 v133, v133 offset:2048
	ds_read_b32 v134, v134 offset:2048
	ds_read_b32 v135, v135 offset:2048
	ds_read_b32 v136, v136 offset:2048
	ds_read_b32 v137, v137 offset:2048
	s_add_i32 s34, s34, -16
	v_add_u32_e32 v11, 64, v11
	s_cmp_eq_u32 s34, 0
	s_waitcnt lgkmcnt(7)
	v_fmac_f32_e32 v10, v130, v16
	s_waitcnt lgkmcnt(6)
	v_fmac_f32_e32 v10, v131, v17
	s_waitcnt lgkmcnt(5)
	v_fmac_f32_e32 v10, v132, v18
	s_waitcnt lgkmcnt(4)
	v_fmac_f32_e32 v10, v133, v19
	s_waitcnt lgkmcnt(3)
	v_fmac_f32_e32 v10, v134, v20
	s_waitcnt lgkmcnt(2)
	v_fmac_f32_e32 v10, v135, v21
	s_waitcnt lgkmcnt(1)
	v_fmac_f32_e32 v10, v136, v22
	s_waitcnt lgkmcnt(0)
	v_fmac_f32_e32 v10, v137, v23
	v_add_u32_e32 v138, 0xfffffef8, v12
	v_add_u32_e32 v139, 0xfffffef7, v12
	v_add_u32_e32 v140, 0xfffffef6, v12
	v_add_u32_e32 v141, 0xfffffef5, v12
	v_add_u32_e32 v142, 0xfffffef4, v12
	v_add_u32_e32 v143, 0xfffffef3, v12
	v_add_u32_e32 v144, 0xfffffef2, v12
	v_add_u32_e32 v145, 0xfffffef1, v12
	v_and_b32_e32 v138, 0x1ff, v138
	v_and_b32_e32 v139, 0x1ff, v139
	v_and_b32_e32 v140, 0x1ff, v140
	v_and_b32_e32 v141, 0x1ff, v141
	v_and_b32_e32 v142, 0x1ff, v142
	v_and_b32_e32 v143, 0x1ff, v143
	v_and_b32_e32 v144, 0x1ff, v144
	v_and_b32_e32 v145, 0x1ff, v145
	v_lshl_add_u32 v138, v138, 2, 0
	v_lshl_add_u32 v139, v139, 2, 0
	v_lshl_add_u32 v140, v140, 2, 0
	v_lshl_add_u32 v141, v141, 2, 0
	v_lshl_add_u32 v142, v142, 2, 0
	v_lshl_add_u32 v143, v143, 2, 0
	v_lshl_add_u32 v144, v144, 2, 0
	v_lshl_add_u32 v145, v145, 2, 0
	ds_read_b32 v138, v138 offset:2048
	ds_read_b32 v139, v139 offset:2048
	ds_read_b32 v140, v140 offset:2048
	ds_read_b32 v141, v141 offset:2048
	ds_read_b32 v142, v142 offset:2048
	ds_read_b32 v143, v143 offset:2048
	ds_read_b32 v144, v144 offset:2048
	ds_read_b32 v145, v145 offset:2048
	s_waitcnt lgkmcnt(7)
	v_fmac_f32_e32 v10, v138, v24
	s_waitcnt lgkmcnt(6)
	v_fmac_f32_e32 v10, v139, v25
	s_waitcnt lgkmcnt(5)
	v_fmac_f32_e32 v10, v140, v26
	s_waitcnt lgkmcnt(4)
	v_fmac_f32_e32 v10, v141, v27
	s_waitcnt lgkmcnt(3)
	v_fmac_f32_e32 v10, v142, v28
	s_waitcnt lgkmcnt(2)
	v_fmac_f32_e32 v10, v143, v29
	s_waitcnt lgkmcnt(1)
	v_fmac_f32_e32 v10, v144, v30
	s_waitcnt lgkmcnt(0)
	v_fmac_f32_e32 v10, v145, v31
	s_cbranch_scc0 .LBB0_327
	v_fmac_f32_e32 v10, v5, v9
	v_mul_f32_e32 v8, v8, v10
	v_lshlrev_b64 v[6:7], 9, v[6:7]
	v_cvt_pk_bf16_f32 v8, v8, s0
	v_lshl_add_u64 v[6:7], s[10:11], 0, v[6:7]
	s_movk_i32 s79, 0x200
	s_mov_b64 s[34:35], 0
	s_and_b64 vcc, exec, s[30:31]
	global_store_short v[6:7], v8, off
	s_cbranch_vccz .LBB0_312
	s_barrier
	s_mov_b64 s[0:1], 0
